# w_down transposes moved from P0 into the P1 K-loop (rotating 32-register window, 2 loads per iteration, pack+store in the tile epilogue); peel; epilogue prefetch
# speedup vs baseline: 1.0052x; 1.0036x over previous
; #define GAS __attribute__((address_space(1)))
; #define LAS __attribute__((address_space(3)))
; #define LDS_WAIT() asm volatile("s_waitcnt lgkmcnt(0)" ::: "memory")
; __device__ __forceinline__ void p0_transpose_item(const float* W, int ldw, int col_off, int K, int N, const float* rs, bf16_t* WT, LAS float* scr, int item, int lane) {
;     const int nblk = N / 32, kb = item / nblk, nb = item % nblk, k0 = 64 * kb, n0 = 32 * nb;
;     const int r8 = lane >> 3, c4 = (lane & 7) * 4;
;     f32x4 v[8]; float sc[8];
; #pragma unroll
;     for (int i = 0; i < 8; ++i) { const int kk = 8 * i + r8; v[i] = __builtin_nontemporal_load((const GAS f32x4*)(W + (size_t)(k0 + kk) * ldw + col_off + n0 + c4)); sc[i] = rs ? rs[k0 + kk] : 1.0f; }
; #pragma unroll
;     for (int i = 0; i < 8; ++i) { LAS float* d = scr + (8 * i + r8) * 33 + c4; d[0] = v[i].x * sc[i]; d[1] = v[i].y * sc[i]; d[2] = v[i].z * sc[i]; d[3] = v[i].w * sc[i]; }
;     LDS_WAIT();
;     const int c = lane & 7;
; #pragma unroll
;     for (int j = 0; j < 4; ++j) { const int n = (lane >> 3) + 8 * j; const LAS float* s = scr + (8 * c) * 33 + n;
;         v4u o; o.x = pk2(s[0 * 33], s[1 * 33]); o.y = pk2(s[2 * 33], s[3 * 33]); o.z = pk2(s[4 * 33], s[5 * 33]); o.w = pk2(s[6 * 33], s[7 * 33]);
;         *(GAS v4u*)(WT + (size_t)(n0 + n) * K + k0 + 8 * c) = o; }
;     LDS_WAIT();
; }
; __global__ void __launch_bounds__(NWAVES * 64, 2) mk_fwd(Args args) {
;     ...
;             constexpr int I_QKV = (2048 / 64) * (3072 / 32), I_U = (2048 / 64) * (1024 / 32), I_O = (2048 / 64) * (2048 / 32), I_UP = (2048 / 64) * (8192 / 32), I_D = (8192 / 64) * (2048 / 32);
;             constexpr int NITEMS = I_QKV + I_U + I_O + I_UP + I_D;
;             for (int it = gw; it < NITEMS; it += NGW) {
;                 int r = it;
;                 if (r < I_QKV) { p0_transpose_item(w_in, 4096, 1024, 2048, 3072, g_mix, wint, scr, r, lane); continue; } r -= I_QKV;
;                 if (r < I_U) { p0_transpose_item(w_in, 4096, 0, 2048, 1024, g_mix, wint + (size_t)3072 * 2048, scr, r, lane); continue; } r -= I_U;
;                 if (r < I_O) { p0_transpose_item_wo(w_out, wo, scr, r, lane); continue; } r -= I_O;
;                 if (r < I_UP) { p0_transpose_item(w_up, 8192, 0, 2048, 8192, g_mlp, wup, scr, r, lane); continue; } r -= I_UP;
;                 p0_transpose_item(w_down, 2048, 0, 8192, 2048, nullptr, wd, scr, r, lane);
;             }
.LBB0_26:
	s_or_b64 exec, exec, s[8:9]
	s_add_u32 s0, s94, 0x1c00000
	s_addc_u32 s1, s95, 0
	s_add_u32 s62, s94, 0x4400000
	s_addc_u32 s63, s95, 0
	s_add_u32 s24, s94, 0x400000
	s_addc_u32 s25, s95, 0
	s_add_u32 s64, s94, 0x2400000
	v_writelane_b32 v254, s0, 10
	s_addc_u32 s65, s95, 0
	s_movk_i32 s99, 0x57ff
	s_cmp_lg_u32 s96, 0x800
	s_cbranch_scc1 .Lwd_p0_all
	s_movk_i32 s99, 0x37ff
.Lwd_p0_all:
	s_cmp_gt_i32 s38, s99
	v_writelane_b32 v254, s1, 11
	s_cbranch_scc1 .LBB0_109
	v_lshrrev_b32_e32 v55, 3, v1
	v_and_b32_e32 v0, 7, v0
	v_lshlrev_b32_e32 v32, 4, v0
	v_mov_b32_e32 v33, 0
	v_lshlrev_b32_e32 v36, 3, v0
	v_mul_u32_u24_e32 v0, 0x420, v0
	v_lshlrev_b32_e32 v1, 2, v55
	v_add3_u32 v65, s83, v0, v1
	s_cmp_lg_u64 s[18:19], 0
	v_lshl_add_u64 v[0:1], s[94:95], 0, v[32:33]
	s_mov_b64 s[0:1], 0x1000000
	v_add_u32_e32 v2, s83, v32
	v_mul_u32_u24_e32 v3, 0x84, v55
	s_cselect_b64 s[4:5], -1, 0
	v_lshl_add_u64 v[46:47], s[12:13], 0, v[32:33]
	s_cmp_lg_u64 s[10:11], 0
	v_lshl_add_u64 v[48:49], v[0:1], 0, s[0:1]
	s_mov_b64 s[0:1], 0x1000
	s_cselect_b64 s[6:7], -1, 0
	v_lshl_add_u64 v[50:51], v[46:47], 0, s[0:1]
	s_lshl_b32 s0, s38, 1
	v_add_u32_e32 v67, v2, v3
	v_lshl_add_u64 v[34:35], s[22:23], 0, v[32:33]
	v_or_b32_e32 v59, 8, v55
	v_or_b32_e32 v61, 16, v55
	v_or_b32_e32 v63, 24, v55
	v_mov_b32_e32 v37, v33
	v_lshl_add_u64 v[38:39], s[62:63], 0, v[32:33]
	v_lshl_add_u64 v[40:41], s[20:21], 0, v[32:33]
	v_lshl_add_u64 v[42:43], s[64:65], 0, v[32:33]
	v_lshl_add_u64 v[44:45], s[16:17], 0, v[32:33]
	v_lshl_add_u64 v[52:53], s[24:25], 0, v[32:33]
	s_lshl_b32 s13, s38, 5
	s_lshl_b32 s14, s96, 5
	s_add_i32 s15, s0, 0x1e800
	s_lshl_b32 s22, s96, 1
	s_mov_b32 s9, 0
	v_add_u32_e32 v69, 0x420, v67
	v_add_u32_e32 v70, 0x428, v67
	v_add_u32_e32 v71, 0x840, v67
	v_add_u32_e32 v72, 0x848, v67
	v_add_u32_e32 v73, 0xc60, v67
	v_add_u32_e32 v74, 0xc68, v67
	v_add_u32_e32 v75, 0x1080, v67
	v_add_u32_e32 v76, 0x1088, v67
	v_add_u32_e32 v77, 0x14a0, v67
	v_add_u32_e32 v78, 0x14a8, v67
	v_add_u32_e32 v79, 0x18c0, v67
	v_add_u32_e32 v80, 0x18c8, v67
	v_add_u32_e32 v81, 0x1ce0, v67
	v_add_u32_e32 v82, 0x1ce8, v67
	s_mov_b32 s12, 0x42000000
	v_mov_b32_e32 v83, 0x40000
	v_mov_b32_e32 v84, 0x80000
	v_mov_b32_e32 v85, 0xc0000
	v_mov_b32_e32 v86, 0x100000
	v_mov_b32_e32 v87, 0x140000
	v_mov_b32_e32 v88, 0x180000
	v_mov_b32_e32 v89, 0x1c0000
	v_mov_b32_e32 v90, 0x20000
	v_mov_b32_e32 v91, 0x60000
	v_mov_b32_e32 v92, 0xa0000
	v_mov_b32_e32 v93, 0xe0000
	s_mov_b32 s23, s38
	s_branch .LBB0_30

; __global__ void __launch_bounds__(NWAVES * 64, 2) mk_fwd(Args args) {
;     ...
;             for (int it = gw; it < NITEMS; it += NGW) {
;                 int r = it;
;                 if (r < I_QKV) { p0_transpose_item(w_in, 4096, 1024, 2048, 3072, g_mix, wint, scr, r, lane); continue; } r -= I_QKV;
;                 if (r < I_U) { p0_transpose_item(w_in, 4096, 0, 2048, 1024, g_mix, wint + (size_t)3072 * 2048, scr, r, lane); continue; } r -= I_U;
;                 if (r < I_O) { p0_transpose_item_wo(w_out, wo, scr, r, lane); continue; } r -= I_O;
;                 if (r < I_UP) { p0_transpose_item(w_up, 8192, 0, 2048, 8192, g_mlp, wup, scr, r, lane); continue; } r -= I_UP;
;                 p0_transpose_item(w_down, 2048, 0, 8192, 2048, nullptr, wd, scr, r, lane);
;             }
.LBB0_29:
	s_add_i32 s23, s23, s96
	s_add_i32 s13, s13, s14
	s_add_i32 s15, s15, s22
	s_cmp_gt_i32 s23, s99
	s_cbranch_scc1 .LBB0_109

;     __device__ __forceinline__ unsigned voffA(int R, int C) const { return (unsigned)(R * lda + C) * 2u; }
;     __device__ __forceinline__ unsigned voffB(int R, int C) const { return (unsigned)(R * ldb + C) * 2u; }
;     __device__ __forceinline__ unsigned voffA(int R, int C) const { return (unsigned)(R * 256 + C) * 2u; }
;     __device__ __forceinline__ unsigned voffB(int R, int C) const { return (unsigned)((256 * (R & 15) + (R >> 4)) * 1024 + C) * 2u; }
;     __device__ __forceinline__ unsigned voffA(int R, int C) const { return (unsigned)(R * 512 + C) * 2u; }
;     __device__ __forceinline__ unsigned voffB(int R, int C) const { return (unsigned)(R * 8192 + C) * 2u; }
; #define PG8_STAGE(bufoff, gbase, voff) do { _Pragma("unroll") for (int _i = 0; _i < 2; ++_i) { const unsigned _vo = (voff)[_i]; \
;         __builtin_amdgcn_global_load_lds((const PG8_GAS unsigned*)((const PG8_GAS char*)(gbase) + _vo), (PG8_LAS unsigned*)(lds + (bufoff) + ldsw + _i * 8192), 16, 0, 0); } } while (0)
; #define PG8_WAIT_V(n) asm volatile("s_waitcnt vmcnt(" #n ")" ::: "memory")
; #define PG8_BAR __builtin_amdgcn_s_barrier()
;     ...
;     const unsigned ldsw = (unsigned)wid * 1024u;
;     const int aoff = lds_byte(wr * 64 + fr, fq * 8), boff = lds_byte(wc * 32 + fr, fq * 8);
;     ...
;     PG8_STAGE(PG8_SB(0, 0), cB, voffB); PG8_STAGE(PG8_SB(0, 1), cB + hstepB, voffB); PG8_STAGE(PG8_SA(0, 0), cA, voffA); PG8_STAGE(PG8_SA(0, 1), cA + hstepA, voffA);
;     if (wr == 1) PG8_BAR;
;     PG8_WAIT_V(2); PG8_BAR;
;     PG8_STAGE(PG8_SB(1, 0), cB + kstep, voffB); PG8_STAGE(PG8_SA(1, 0), cA + kstep, voffA); PG8_STAGE(PG8_SB(1, 1), cB + hstepB + kstep, voffB);
;     PG8_WAIT_V(6); PG8_BAR;
.LBB0_172:
	s_add_u32 s12, s94, 0x100000
	s_mov_b64 s[8:9], 0x80
	s_addc_u32 s13, s95, 0
	s_add_i32 m0, s38, 0x18000
	v_lshl_add_u64 v[4:5], v[4:5], 0, s[8:9]
	s_waitcnt vmcnt(2)
	s_barrier
	global_load_lds_dwordx4 v[4:5], off
	v_lshl_add_u64 v[2:3], v[2:3], 0, s[8:9]
	s_add_i32 m0, s38, 0x1a000
	s_add_i32 s14, s38, 0x8000
	global_load_lds_dwordx4 v[2:3], off
	v_lshl_add_u64 v[0:1], v[0:1], 0, s[8:9]
	s_mov_b32 m0, s14
	s_add_i32 s15, s38, 0xa000
	global_load_lds_dwordx4 v[0:1], off
	v_lshl_add_u64 v[0:1], v[6:7], 0, s[8:9]
	s_add_u32 s8, s30, 0x80080
	s_mov_b32 m0, s15
	s_addc_u32 s9, s31, 0
	global_load_lds_dwordx4 v[0:1], off
	s_add_i32 m0, s38, 0x1c000
	v_lshl_add_u64 v[0:1], s[8:9], 0, v[130:131]
	global_load_lds_dwordx4 v[0:1], off
	v_lshl_add_u64 v[0:1], s[8:9], 0, v[134:135]
	s_add_i32 m0, s38, 0x1e000
	v_and_b32_e32 v4, 48, v8
	global_load_lds_dwordx4 v[0:1], off
	v_and_b32_e32 v0, 15, v8
	v_or_b32_e32 v1, s48, v0
	v_lshlrev_b32_e32 v3, 6, v1
	s_movk_i32 s5, 0x3c0
	v_ashrrev_i32_e32 v2, 6, v8
	v_and_or_b32 v3, v3, s5, v4
	v_readlane_b32 s5, v254, 18
	v_lshlrev_b32_e32 v1, 2, v1
	v_and_b32_e32 v1, 32, v1
	v_lshl_add_u32 v5, v2, 10, s5
	v_readlane_b32 s5, v254, 19
	v_bitop3_b32 v1, v3, v5, v1 bitop3:0xde
	v_lshlrev_b32_e32 v3, 2, v8
	v_add_lshl_u32 v2, v2, s5, 10
	v_readlane_b32 s5, v254, 14
	v_lshl_or_b32 v0, v0, 6, v4
	v_and_b32_e32 v3, 32, v3
	s_waitcnt vmcnt(6)
	s_cmpk_lt_u32 s5, 0x100
	v_bitop3_b32 v129, v0, v2, v3 bitop3:0xde
	s_cselect_b64 s[16:17], -1, 0
	s_add_i32 s57, 0, 0x10000
	s_add_i32 s60, 0, 0x14000
	s_ashr_i32 s55, s3, 31
	s_ashr_i32 s56, s2, 31
	v_mov_b64_e32 v[136:137], 0x400
	v_mov_b64_e32 v[138:139], 0x3ff
	v_add_u32_e32 v133, s57, v129
	v_add_u32_e32 v135, s60, v129
	v_add_u32_e32 v164, 0, v1
	v_mov_b32_e32 v165, 0x3e0293ee
	v_mov_b32_e32 v166, v130
	s_barrier
	v_lshrrev_b32_e32 v250, 5, v8
	v_and_b32_e32 v251, 31, v8
	v_lshlrev_b32_e32 v250, 18, v250
	v_lshl_or_b32 v250, v251, 2, v250
	v_add_u32_e32 v251, 0x2000, v250
	v_readlane_b32 s98, v254, 0
	v_readlane_b32 s99, v254, 1
	s_sub_u32 s98, s98, 0x58
	s_subb_u32 s99, s99, 0
	s_load_dwordx2 s[100:101], s[98:99], 0x38
	s_waitcnt lgkmcnt(0)
	v_writelane_b32 v252, s100, 0
	v_writelane_b32 v252, s101, 1
	s_add_u32 s98, s94, 0x4400000
	s_addc_u32 s99, s95, 0
	v_writelane_b32 v252, s98, 2
	v_writelane_b32 v252, s99, 3
	s_lshl_b32 s98, s2, 3
	s_add_i32 s98, s98, s49
	s_and_b32 s98, s98, 0x7ff
	v_writelane_b32 v252, s98, 5
	s_branch .LBB0_175

;     __device__ __forceinline__ const char* a(const Unit& u) const { return (const char*)A + (size_t)u.pm * 2 * hA(); }
;     __device__ __forceinline__ const char* b(const Unit& u) const { return (const char*)Bt + (size_t)u.pn * 2 * hB() + (size_t)(u.pm >> gshift) * goff; }
;     __device__ __forceinline__ const char* a(const Unit& u) const { return (const char*)A + (size_t)u.pm * 2 * hA(); }
;     __device__ __forceinline__ const char* b(const Unit& u) const { return (const char*)Bt + (size_t)((u.pn >> 4) * 4096 + (u.pn & 15) * 16) * 1024 * 2 + (size_t)(u.pm >> 1) * 512; }
;     __device__ __forceinline__ const char* a(const Unit&) const { return (const char*)A; }
;     __device__ __forceinline__ const char* b(const Unit& u) const { return (const char*)Bt + ((size_t)(((u.pm >> 4) * 1024 + u.pn * 256) * 16 + (u.pm & 15)) * 512) * 2; }
;     ...
; #pragma unroll
;         for (int a = 0; a < 2; ++a)
; #pragma unroll
;             for (int b = 0; b < 2; ++b)
; #pragma unroll
;                 for (int m = 0; m < 4; ++m)
; #pragma unroll
;                     for (int n = 0; n < 2; ++n) acc[a][b][m][n] = (f32x4){0.f, 0.f, 0.f, 0.f};
;         cur = nxt; cA = nA; cB = nB; ++ui;
.LBB0_181:
	s_ashr_i32 s21, s20, 31
	s_lshl_b64 s[22:23], s[20:21], 20
	v_readlane_b32 s26, v254, 20
	v_readlane_b32 s27, v254, 21
	s_add_u32 s22, s26, s22
	s_addc_u32 s23, s27, s23
	s_and_b64 s[26:27], s[8:9], exec
	s_cselect_b32 s5, s23, s29
	s_cselect_b32 s7, s22, s28
	s_ashr_i32 s19, s18, 31
	s_lshl_b64 s[26:27], s[18:19], 20
	s_add_u32 s26, s24, s26
	s_addc_u32 s27, s25, s27
	s_and_b64 s[34:35], s[8:9], exec
	s_cselect_b32 s19, s27, s31
	s_cselect_b32 s21, s26, s30
	s_add_u32 s61, s30, 0x100
	v_mov_b32_e32 v0, 0
	s_addc_u32 s66, s31, 0
	s_mov_b32 s67, -2
	v_mov_b32_e32 v1, v0
	v_mov_b32_e32 v2, v0
	v_mov_b32_e32 v3, v0
	v_mov_b32_e32 v4, v0
	v_mov_b32_e32 v5, v0
	v_mov_b32_e32 v6, v0
	v_mov_b32_e32 v7, v0
	v_mov_b32_e32 v16, v0
	v_mov_b32_e32 v17, v0
	v_mov_b32_e32 v18, v0
	v_mov_b32_e32 v19, v0
	v_mov_b32_e32 v20, v0
	v_mov_b32_e32 v21, v0
	v_mov_b32_e32 v22, v0
	v_mov_b32_e32 v23, v0
	v_mov_b32_e32 v32, v0
	v_mov_b32_e32 v33, v0
	v_mov_b32_e32 v34, v0
	v_mov_b32_e32 v35, v0
	v_mov_b32_e32 v36, v0
	v_mov_b32_e32 v37, v0
	v_mov_b32_e32 v38, v0
	v_mov_b32_e32 v39, v0
	v_mov_b32_e32 v48, v0
	v_mov_b32_e32 v49, v0
	v_mov_b32_e32 v50, v0
	v_mov_b32_e32 v51, v0
	v_mov_b32_e32 v52, v0
	v_mov_b32_e32 v53, v0
	v_mov_b32_e32 v54, v0
	v_mov_b32_e32 v55, v0
	v_mov_b32_e32 v8, v0
	v_mov_b32_e32 v9, v0
	v_mov_b32_e32 v10, v0
	v_mov_b32_e32 v11, v0
	v_mov_b32_e32 v12, v0
	v_mov_b32_e32 v13, v0
	v_mov_b32_e32 v14, v0
	v_mov_b32_e32 v15, v0
	v_mov_b32_e32 v24, v0
	v_mov_b32_e32 v25, v0
	v_mov_b32_e32 v26, v0
	v_mov_b32_e32 v27, v0
	v_mov_b32_e32 v28, v0
	v_mov_b32_e32 v29, v0
	v_mov_b32_e32 v30, v0
	v_mov_b32_e32 v31, v0
	v_mov_b32_e32 v40, v0
	v_mov_b32_e32 v41, v0
	v_mov_b32_e32 v42, v0
	v_mov_b32_e32 v43, v0
	v_mov_b32_e32 v44, v0
	v_mov_b32_e32 v45, v0
	v_mov_b32_e32 v46, v0
	v_mov_b32_e32 v47, v0
	v_mov_b32_e32 v56, v0
	v_mov_b32_e32 v57, v0
	v_mov_b32_e32 v58, v0
	v_mov_b32_e32 v59, v0
	v_mov_b32_e32 v60, v0
	v_mov_b32_e32 v61, v0
	v_mov_b32_e32 v62, v0
	v_mov_b32_e32 v63, v0
	v_mov_b32_e32 v64, v0
	v_mov_b32_e32 v65, v0
	v_mov_b32_e32 v66, v0
	v_mov_b32_e32 v67, v0
	v_mov_b32_e32 v68, v0
	v_mov_b32_e32 v69, v0
	v_mov_b32_e32 v70, v0
	v_mov_b32_e32 v71, v0
	v_mov_b32_e32 v80, v0
	v_mov_b32_e32 v81, v0
	v_mov_b32_e32 v82, v0
	v_mov_b32_e32 v83, v0
	v_mov_b32_e32 v84, v0
	v_mov_b32_e32 v85, v0
	v_mov_b32_e32 v86, v0
	v_mov_b32_e32 v87, v0
	v_mov_b32_e32 v96, v0
	v_mov_b32_e32 v97, v0
	v_mov_b32_e32 v98, v0
	v_mov_b32_e32 v99, v0
	v_mov_b32_e32 v100, v0
	v_mov_b32_e32 v101, v0
	v_mov_b32_e32 v102, v0
	v_mov_b32_e32 v103, v0
	v_mov_b32_e32 v112, v0
	v_mov_b32_e32 v113, v0
	v_mov_b32_e32 v114, v0
	v_mov_b32_e32 v115, v0
	v_mov_b32_e32 v116, v0
	v_mov_b32_e32 v117, v0
	v_mov_b32_e32 v118, v0
	v_mov_b32_e32 v119, v0
	v_mov_b32_e32 v72, v0
	v_mov_b32_e32 v73, v0
	v_mov_b32_e32 v74, v0
	v_mov_b32_e32 v75, v0
	v_mov_b32_e32 v76, v0
	v_mov_b32_e32 v77, v0
	v_mov_b32_e32 v78, v0
	v_mov_b32_e32 v79, v0
	v_mov_b32_e32 v88, v0
	v_mov_b32_e32 v89, v0
	v_mov_b32_e32 v90, v0
	v_mov_b32_e32 v91, v0
	v_mov_b32_e32 v92, v0
	v_mov_b32_e32 v93, v0
	v_mov_b32_e32 v94, v0
	v_mov_b32_e32 v95, v0
	v_mov_b32_e32 v104, v0
	v_mov_b32_e32 v105, v0
	v_mov_b32_e32 v106, v0
	v_mov_b32_e32 v107, v0
	v_mov_b32_e32 v108, v0
	v_mov_b32_e32 v109, v0
	v_mov_b32_e32 v110, v0
	v_mov_b32_e32 v111, v0
	v_mov_b32_e32 v120, v0
	v_mov_b32_e32 v121, v0
	v_mov_b32_e32 v122, v0
	v_mov_b32_e32 v123, v0
	v_mov_b32_e32 v124, v0
	v_mov_b32_e32 v125, v0
	v_mov_b32_e32 v126, v0
	v_mov_b32_e32 v127, v0
	v_readlane_b32 s98, v252, 5
	s_sub_i32 s99, s54, 1
	s_lshl_b32 s99, s99, 11
	s_add_i32 s98, s98, s99
	s_and_b32 s98, s98, 0x1fff
	s_lshr_b32 s99, s98, 6
	s_and_b32 s98, s98, 63
	s_lshl_b32 s99, s99, 19
	s_lshl_b32 s98, s98, 7
	s_add_u32 s98, s98, s99
	v_readlane_b32 s100, v252, 0
	v_readlane_b32 s101, v252, 1
	s_add_u32 s98, s100, s98
	s_addc_u32 s99, s101, 0
	s_cmp_lt_u32 s54, 2
	s_cbranch_scc1 .LBB0_182
	s_add_u32 s30, s28, 0x100
	s_addc_u32 s31, s29, 0
	s_cmp_eq_u32 s67, 28
	s_cselect_b32 s42, s7, s30
	s_cselect_b32 s43, s5, s31
	s_cselect_b32 s45, s19, s66
	s_cselect_b32 s44, s21, s61
	s_add_u32 s34, s42, 0x80
	s_addc_u32 s35, s43, 0
	s_add_u32 s36, s44, 0x80
	s_addc_u32 s37, s45, 0
	s_add_u32 s68, s28, 0x80080
	s_addc_u32 s69, s29, 0
	s_add_u32 s40, s42, 0x80000
	s_addc_u32 s41, s43, 0
	s_add_u32 s46, s44, 0x80000
	s_addc_u32 s47, s45, 0
	s_add_u32 s28, s44, 0x80080
	s_addc_u32 s29, s45, 0
	ds_read_b128 v[140:143], v133
	ds_read_b128 v[144:147], v133 offset:1024
	ds_read_b128 v[148:151], v133 offset:2048
	ds_read_b128 v[152:155], v133 offset:3072
	ds_read_b128 v[156:159], v135
	ds_read_b128 v[160:163], v135 offset:1024
	ds_read_b128 v[168:171], v135 offset:2048
	ds_read_b128 v[172:175], v135 offset:3072
	s_add_i32 m0, s38, 0xc000
	ds_read_b128 v[176:179], v164
	ds_read_b128 v[180:183], v164 offset:1024
	ds_read_b128 v[184:187], v164 offset:2048
	ds_read_b128 v[188:191], v164 offset:3072
	ds_read_b128 v[192:195], v164 offset:4096
	ds_read_b128 v[196:199], v164 offset:5120
	ds_read_b128 v[200:203], v164 offset:6144
	ds_read_b128 v[204:207], v164 offset:7168
	global_load_lds_dwordx4 v128, s[68:69]
	s_add_i32 m0, s38, 0xe000
	s_nop 0
	global_load_lds_dwordx4 v132, s[68:69]
	s_waitcnt vmcnt(36)
	s_waitcnt lgkmcnt(0)
	s_barrier
	s_setprio 1
	s_waitcnt lgkmcnt(0)
	v_mfma_f32_16x16x32_bf16 v[124:127], v[140:143], v[176:179], v[124:127]
	v_mov_b32_e32 v208, v210
	v_mfma_f32_16x16x32_bf16 v[120:123], v[148:151], v[176:179], v[120:123]
	v_mov_b32_e32 v209, v211
	v_mfma_f32_16x16x32_bf16 v[108:111], v[140:143], v[184:187], v[108:111]
	v_mov_b32_e32 v210, v212
	v_mfma_f32_16x16x32_bf16 v[104:107], v[148:151], v[184:187], v[104:107]
	v_mov_b32_e32 v211, v213
	v_mfma_f32_16x16x32_bf16 v[92:95], v[140:143], v[192:195], v[92:95]
	v_mov_b32_e32 v212, v214
	v_mfma_f32_16x16x32_bf16 v[88:91], v[148:151], v[192:195], v[88:91]
	v_mov_b32_e32 v213, v215
	v_mfma_f32_16x16x32_bf16 v[76:79], v[140:143], v[200:203], v[76:79]
	v_mov_b32_e32 v214, v216
	v_mfma_f32_16x16x32_bf16 v[72:75], v[148:151], v[200:203], v[72:75]
	v_mov_b32_e32 v215, v217
	v_mfma_f32_16x16x32_bf16 v[124:127], v[144:147], v[180:183], v[124:127]
	v_mov_b32_e32 v216, v218
	v_mfma_f32_16x16x32_bf16 v[120:123], v[152:155], v[180:183], v[120:123]
	v_mov_b32_e32 v217, v219
	v_mfma_f32_16x16x32_bf16 v[108:111], v[144:147], v[188:191], v[108:111]
	v_mov_b32_e32 v218, v220
	v_mfma_f32_16x16x32_bf16 v[104:107], v[152:155], v[188:191], v[104:107]
	v_mov_b32_e32 v219, v221
	v_mfma_f32_16x16x32_bf16 v[92:95], v[144:147], v[196:199], v[92:95]
	v_mov_b32_e32 v220, v222
	v_mfma_f32_16x16x32_bf16 v[88:91], v[152:155], v[196:199], v[88:91]
	v_mov_b32_e32 v221, v223
	v_mfma_f32_16x16x32_bf16 v[76:79], v[144:147], v[204:207], v[76:79]
	v_mov_b32_e32 v222, v224
	v_mfma_f32_16x16x32_bf16 v[72:75], v[152:155], v[204:207], v[72:75]
	v_mov_b32_e32 v223, v225
	s_setprio 0
	s_setprio 1
	v_mfma_f32_16x16x32_bf16 v[116:119], v[156:159], v[176:179], v[116:119]
	v_mov_b32_e32 v224, v226
	v_mfma_f32_16x16x32_bf16 v[112:115], v[168:171], v[176:179], v[112:115]
	v_mov_b32_e32 v225, v227
	v_mfma_f32_16x16x32_bf16 v[100:103], v[156:159], v[184:187], v[100:103]
	v_mov_b32_e32 v226, v228
	v_mfma_f32_16x16x32_bf16 v[96:99], v[168:171], v[184:187], v[96:99]
	v_mov_b32_e32 v227, v229
	v_mfma_f32_16x16x32_bf16 v[84:87], v[156:159], v[192:195], v[84:87]
	v_mov_b32_e32 v228, v230
	v_mfma_f32_16x16x32_bf16 v[80:83], v[168:171], v[192:195], v[80:83]
	v_mov_b32_e32 v229, v231
	v_mfma_f32_16x16x32_bf16 v[68:71], v[156:159], v[200:203], v[68:71]
	v_mov_b32_e32 v230, v232
	v_mfma_f32_16x16x32_bf16 v[64:67], v[168:171], v[200:203], v[64:67]
	v_mov_b32_e32 v231, v233
	v_mfma_f32_16x16x32_bf16 v[116:119], v[160:163], v[180:183], v[116:119]
	v_mov_b32_e32 v232, v234
	v_mfma_f32_16x16x32_bf16 v[112:115], v[172:175], v[180:183], v[112:115]
	v_mov_b32_e32 v233, v235
	v_mfma_f32_16x16x32_bf16 v[100:103], v[160:163], v[188:191], v[100:103]
	v_mov_b32_e32 v234, v236
	v_mfma_f32_16x16x32_bf16 v[96:99], v[172:175], v[188:191], v[96:99]
	v_mov_b32_e32 v235, v237
	v_mfma_f32_16x16x32_bf16 v[84:87], v[160:163], v[196:199], v[84:87]
	v_mov_b32_e32 v236, v238
	v_mfma_f32_16x16x32_bf16 v[80:83], v[172:175], v[196:199], v[80:83]
	v_mov_b32_e32 v237, v239
	v_mfma_f32_16x16x32_bf16 v[68:71], v[160:163], v[204:207], v[68:71]
	v_mfma_f32_16x16x32_bf16 v[64:67], v[172:175], v[204:207], v[64:67]
	s_setprio 0
	s_barrier
	s_add_i32 s68, s57, s33
	s_mov_b32 m0, s68
	ds_read_b128 v[176:179], v164 offset:16384
	ds_read_b128 v[180:183], v164 offset:17408
	ds_read_b128 v[184:187], v164 offset:18432
	ds_read_b128 v[188:191], v164 offset:19456
	ds_read_b128 v[192:195], v164 offset:20480
	ds_read_b128 v[196:199], v164 offset:21504
	ds_read_b128 v[200:203], v164 offset:22528
	ds_read_b128 v[204:207], v164 offset:23552
	global_load_lds_dwordx4 v166, s[44:45]
	s_add_i32 m0, s68, 0x2000
	s_nop 0
	global_load_lds_dwordx4 v134, s[44:45]
	s_add_i32 s44, s60, s33
	s_mov_b32 m0, s44
	s_nop 0
	global_load_lds_dwordx4 v166, s[46:47]
	s_add_i32 m0, s44, 0x2000
	s_nop 0
	global_load_lds_dwordx4 v134, s[46:47]
	s_mov_b32 m0, s38
	s_nop 0
	global_load_lds_dwordx4 v128, s[42:43]
	s_mov_b32 m0, s39
	s_nop 0
	global_load_lds_dwordx4 v132, s[42:43]
	global_load_dword v238, v250, s[98:99]
	global_load_dword v239, v251, s[98:99]
	s_add_u32 s98, s98, 0x4000
	s_addc_u32 s99, s99, 0
	s_waitcnt vmcnt(38)
	s_waitcnt lgkmcnt(0)
	s_barrier
	s_setprio 1
	s_waitcnt lgkmcnt(0)
	v_mfma_f32_16x16x32_bf16 v[60:63], v[140:143], v[176:179], v[60:63]
	v_mfma_f32_16x16x32_bf16 v[56:59], v[148:151], v[176:179], v[56:59]
	v_mfma_f32_16x16x32_bf16 v[44:47], v[140:143], v[184:187], v[44:47]
	v_mfma_f32_16x16x32_bf16 v[40:43], v[148:151], v[184:187], v[40:43]
	v_mfma_f32_16x16x32_bf16 v[28:31], v[140:143], v[192:195], v[28:31]
	v_mfma_f32_16x16x32_bf16 v[24:27], v[148:151], v[192:195], v[24:27]
	v_mfma_f32_16x16x32_bf16 v[12:15], v[140:143], v[200:203], v[12:15]
	v_mfma_f32_16x16x32_bf16 v[8:11], v[148:151], v[200:203], v[8:11]
	v_mfma_f32_16x16x32_bf16 v[60:63], v[144:147], v[180:183], v[60:63]
	v_mfma_f32_16x16x32_bf16 v[56:59], v[152:155], v[180:183], v[56:59]
	v_mfma_f32_16x16x32_bf16 v[44:47], v[144:147], v[188:191], v[44:47]
	v_mfma_f32_16x16x32_bf16 v[40:43], v[152:155], v[188:191], v[40:43]
	v_mfma_f32_16x16x32_bf16 v[28:31], v[144:147], v[196:199], v[28:31]
	v_mfma_f32_16x16x32_bf16 v[24:27], v[152:155], v[196:199], v[24:27]
	v_mfma_f32_16x16x32_bf16 v[12:15], v[144:147], v[204:207], v[12:15]
	v_mfma_f32_16x16x32_bf16 v[8:11], v[152:155], v[204:207], v[8:11]
	s_setprio 0
	s_setprio 1
	v_mfma_f32_16x16x32_bf16 v[52:55], v[156:159], v[176:179], v[52:55]
	v_mfma_f32_16x16x32_bf16 v[48:51], v[168:171], v[176:179], v[48:51]
	v_mfma_f32_16x16x32_bf16 v[36:39], v[156:159], v[184:187], v[36:39]
	v_mfma_f32_16x16x32_bf16 v[32:35], v[168:171], v[184:187], v[32:35]
	v_mfma_f32_16x16x32_bf16 v[20:23], v[156:159], v[192:195], v[20:23]
	v_mfma_f32_16x16x32_bf16 v[16:19], v[168:171], v[192:195], v[16:19]
	v_mfma_f32_16x16x32_bf16 v[4:7], v[156:159], v[200:203], v[4:7]
	v_mfma_f32_16x16x32_bf16 v[0:3], v[168:171], v[200:203], v[0:3]
	v_mfma_f32_16x16x32_bf16 v[52:55], v[160:163], v[180:183], v[52:55]
	v_mfma_f32_16x16x32_bf16 v[48:51], v[172:175], v[180:183], v[48:51]
	v_mfma_f32_16x16x32_bf16 v[36:39], v[160:163], v[188:191], v[36:39]
	v_mfma_f32_16x16x32_bf16 v[32:35], v[172:175], v[188:191], v[32:35]
	v_mfma_f32_16x16x32_bf16 v[20:23], v[160:163], v[196:199], v[20:23]
	v_mfma_f32_16x16x32_bf16 v[16:19], v[172:175], v[196:199], v[16:19]
	v_mfma_f32_16x16x32_bf16 v[4:7], v[160:163], v[204:207], v[4:7]
	v_mfma_f32_16x16x32_bf16 v[0:3], v[172:175], v[204:207], v[0:3]
	s_setprio 0
	s_barrier
	s_add_i32 s42, 0, 0x18000
	v_add_u32_e32 v130, s42, v129
	s_add_i32 s43, 0, 0x1c000
	ds_read_b128 v[140:143], v130
	ds_read_b128 v[144:147], v130 offset:1024
	ds_read_b128 v[148:151], v130 offset:2048
	ds_read_b128 v[152:155], v130 offset:3072
	v_add_u32_e32 v130, s43, v129
	ds_read_b128 v[156:159], v130
	ds_read_b128 v[160:163], v130 offset:1024
	ds_read_b128 v[168:171], v130 offset:2048
	ds_read_b128 v[172:175], v130 offset:3072
	s_mov_b32 m0, s52
	ds_read_b128 v[176:179], v164 offset:32768
	ds_read_b128 v[180:183], v164 offset:33792
	ds_read_b128 v[184:187], v164 offset:34816
	ds_read_b128 v[188:191], v164 offset:35840
	ds_read_b128 v[192:195], v164 offset:36864
	ds_read_b128 v[196:199], v164 offset:37888
	ds_read_b128 v[200:203], v164 offset:38912
	ds_read_b128 v[204:207], v164 offset:39936
	global_load_lds_dwordx4 v128, s[40:41]
	s_mov_b32 m0, s53
	s_nop 0
	global_load_lds_dwordx4 v132, s[40:41]
	s_waitcnt vmcnt(10)
	s_waitcnt lgkmcnt(0)
	s_barrier
	s_setprio 1
	s_waitcnt lgkmcnt(0)
	v_mfma_f32_16x16x32_bf16 v[124:127], v[140:143], v[176:179], v[124:127]
	v_mfma_f32_16x16x32_bf16 v[120:123], v[148:151], v[176:179], v[120:123]
	v_mfma_f32_16x16x32_bf16 v[108:111], v[140:143], v[184:187], v[108:111]
	v_mfma_f32_16x16x32_bf16 v[104:107], v[148:151], v[184:187], v[104:107]
	v_mfma_f32_16x16x32_bf16 v[92:95], v[140:143], v[192:195], v[92:95]
	v_mfma_f32_16x16x32_bf16 v[88:91], v[148:151], v[192:195], v[88:91]
	v_mfma_f32_16x16x32_bf16 v[76:79], v[140:143], v[200:203], v[76:79]
	v_mfma_f32_16x16x32_bf16 v[72:75], v[148:151], v[200:203], v[72:75]
	v_mfma_f32_16x16x32_bf16 v[124:127], v[144:147], v[180:183], v[124:127]
	v_mfma_f32_16x16x32_bf16 v[120:123], v[152:155], v[180:183], v[120:123]
	v_mfma_f32_16x16x32_bf16 v[108:111], v[144:147], v[188:191], v[108:111]
	v_mfma_f32_16x16x32_bf16 v[104:107], v[152:155], v[188:191], v[104:107]
	v_mfma_f32_16x16x32_bf16 v[92:95], v[144:147], v[196:199], v[92:95]
	v_mfma_f32_16x16x32_bf16 v[88:91], v[152:155], v[196:199], v[88:91]
	v_mfma_f32_16x16x32_bf16 v[76:79], v[144:147], v[204:207], v[76:79]
	v_mfma_f32_16x16x32_bf16 v[72:75], v[152:155], v[204:207], v[72:75]
	s_setprio 0
	s_setprio 1
	v_mfma_f32_16x16x32_bf16 v[116:119], v[156:159], v[176:179], v[116:119]
	v_mfma_f32_16x16x32_bf16 v[112:115], v[168:171], v[176:179], v[112:115]
	v_mfma_f32_16x16x32_bf16 v[100:103], v[156:159], v[184:187], v[100:103]
	v_mfma_f32_16x16x32_bf16 v[96:99], v[168:171], v[184:187], v[96:99]
	v_mfma_f32_16x16x32_bf16 v[84:87], v[156:159], v[192:195], v[84:87]
	v_mfma_f32_16x16x32_bf16 v[80:83], v[168:171], v[192:195], v[80:83]
	v_mfma_f32_16x16x32_bf16 v[68:71], v[156:159], v[200:203], v[68:71]
	v_mfma_f32_16x16x32_bf16 v[64:67], v[168:171], v[200:203], v[64:67]
	v_mfma_f32_16x16x32_bf16 v[116:119], v[160:163], v[180:183], v[116:119]
	v_mfma_f32_16x16x32_bf16 v[112:115], v[172:175], v[180:183], v[112:115]
	v_mfma_f32_16x16x32_bf16 v[100:103], v[160:163], v[188:191], v[100:103]
	v_mfma_f32_16x16x32_bf16 v[96:99], v[172:175], v[188:191], v[96:99]
	v_mfma_f32_16x16x32_bf16 v[84:87], v[160:163], v[196:199], v[84:87]
	v_mfma_f32_16x16x32_bf16 v[80:83], v[172:175], v[196:199], v[80:83]
	v_mfma_f32_16x16x32_bf16 v[68:71], v[160:163], v[204:207], v[68:71]
	v_mfma_f32_16x16x32_bf16 v[64:67], v[172:175], v[204:207], v[64:67]
	s_setprio 0
	s_barrier
	s_add_i32 s40, s42, s33
	s_mov_b32 m0, s40
	ds_read_b128 v[176:179], v164 offset:49152
	ds_read_b128 v[180:183], v164 offset:50176
	ds_read_b128 v[184:187], v164 offset:51200
	ds_read_b128 v[188:191], v164 offset:52224
	ds_read_b128 v[192:195], v164 offset:53248
	ds_read_b128 v[196:199], v164 offset:54272
	ds_read_b128 v[200:203], v164 offset:55296
	ds_read_b128 v[204:207], v164 offset:56320
	global_load_lds_dwordx4 v166, s[36:37]
	s_add_i32 m0, s40, 0x2000
	s_nop 0
	global_load_lds_dwordx4 v134, s[36:37]
	s_add_i32 s36, s43, s33
	s_mov_b32 m0, s36
	s_nop 0
	global_load_lds_dwordx4 v166, s[28:29]
	s_add_i32 m0, s36, 0x2000
	s_nop 0
	global_load_lds_dwordx4 v134, s[28:29]
	s_mov_b32 m0, s14
	s_nop 0
	global_load_lds_dwordx4 v128, s[34:35]
	s_mov_b32 m0, s15
	s_nop 0
	global_load_lds_dwordx4 v132, s[34:35]
	s_waitcnt vmcnt(10)
	s_waitcnt lgkmcnt(0)
	s_barrier
	s_setprio 1
	s_waitcnt lgkmcnt(0)
	v_mfma_f32_16x16x32_bf16 v[60:63], v[140:143], v[176:179], v[60:63]
	v_mfma_f32_16x16x32_bf16 v[56:59], v[148:151], v[176:179], v[56:59]
	v_mfma_f32_16x16x32_bf16 v[44:47], v[140:143], v[184:187], v[44:47]
	v_mfma_f32_16x16x32_bf16 v[40:43], v[148:151], v[184:187], v[40:43]
	v_mfma_f32_16x16x32_bf16 v[28:31], v[140:143], v[192:195], v[28:31]
	v_mfma_f32_16x16x32_bf16 v[24:27], v[148:151], v[192:195], v[24:27]
	v_mfma_f32_16x16x32_bf16 v[12:15], v[140:143], v[200:203], v[12:15]
	v_mfma_f32_16x16x32_bf16 v[8:11], v[148:151], v[200:203], v[8:11]
	v_mfma_f32_16x16x32_bf16 v[60:63], v[144:147], v[180:183], v[60:63]
	v_mfma_f32_16x16x32_bf16 v[56:59], v[152:155], v[180:183], v[56:59]
	v_mfma_f32_16x16x32_bf16 v[44:47], v[144:147], v[188:191], v[44:47]
	v_mfma_f32_16x16x32_bf16 v[40:43], v[152:155], v[188:191], v[40:43]
	v_mfma_f32_16x16x32_bf16 v[28:31], v[144:147], v[196:199], v[28:31]
	v_mfma_f32_16x16x32_bf16 v[24:27], v[152:155], v[196:199], v[24:27]
	v_mfma_f32_16x16x32_bf16 v[12:15], v[144:147], v[204:207], v[12:15]
	v_mfma_f32_16x16x32_bf16 v[8:11], v[152:155], v[204:207], v[8:11]
	s_setprio 0
	s_setprio 1
	v_mfma_f32_16x16x32_bf16 v[52:55], v[156:159], v[176:179], v[52:55]
	v_mfma_f32_16x16x32_bf16 v[48:51], v[168:171], v[176:179], v[48:51]
	v_mfma_f32_16x16x32_bf16 v[36:39], v[156:159], v[184:187], v[36:39]
	v_mfma_f32_16x16x32_bf16 v[32:35], v[168:171], v[184:187], v[32:35]
	v_mfma_f32_16x16x32_bf16 v[20:23], v[156:159], v[192:195], v[20:23]
	v_mfma_f32_16x16x32_bf16 v[16:19], v[168:171], v[192:195], v[16:19]
	v_mfma_f32_16x16x32_bf16 v[4:7], v[156:159], v[200:203], v[4:7]
	v_mfma_f32_16x16x32_bf16 v[0:3], v[168:171], v[200:203], v[0:3]
	v_mfma_f32_16x16x32_bf16 v[52:55], v[160:163], v[180:183], v[52:55]
	v_mfma_f32_16x16x32_bf16 v[48:51], v[172:175], v[180:183], v[48:51]
	v_mfma_f32_16x16x32_bf16 v[36:39], v[160:163], v[188:191], v[36:39]
	v_mfma_f32_16x16x32_bf16 v[32:35], v[172:175], v[188:191], v[32:35]
	v_mfma_f32_16x16x32_bf16 v[20:23], v[160:163], v[196:199], v[20:23]
	v_mfma_f32_16x16x32_bf16 v[16:19], v[172:175], v[196:199], v[16:19]
	v_mfma_f32_16x16x32_bf16 v[4:7], v[160:163], v[204:207], v[4:7]
	v_mfma_f32_16x16x32_bf16 v[0:3], v[172:175], v[204:207], v[0:3]
	s_setprio 0
	s_barrier
	s_add_i32 s67, s67, 2
	s_add_u32 s61, s61, 0x100
	s_addc_u32 s66, s66, 0
	s_cmp_gt_u32 s67, 29
	s_mov_b64 s[28:29], s[30:31]
.LBB0_182:
	s_add_u32 s30, s28, 0x100
	s_addc_u32 s31, s29, 0
	s_cmp_eq_u32 s67, 28
	s_cselect_b32 s42, s7, s30
	s_cselect_b32 s43, s5, s31
	s_cselect_b32 s45, s19, s66
	s_cselect_b32 s44, s21, s61
	s_add_u32 s34, s42, 0x80
	s_addc_u32 s35, s43, 0
	s_add_u32 s36, s44, 0x80
	s_addc_u32 s37, s45, 0
	s_add_u32 s68, s28, 0x80080
	s_addc_u32 s69, s29, 0
	s_add_u32 s40, s42, 0x80000
	s_addc_u32 s41, s43, 0
	s_add_u32 s46, s44, 0x80000
	s_addc_u32 s47, s45, 0
	s_add_u32 s28, s44, 0x80080
	s_addc_u32 s29, s45, 0
	ds_read_b128 v[140:143], v133
	ds_read_b128 v[144:147], v133 offset:1024
	ds_read_b128 v[148:151], v133 offset:2048
	ds_read_b128 v[152:155], v133 offset:3072
	ds_read_b128 v[156:159], v135
	ds_read_b128 v[160:163], v135 offset:1024
	ds_read_b128 v[168:171], v135 offset:2048
	ds_read_b128 v[172:175], v135 offset:3072
	s_add_i32 m0, s38, 0xc000
	ds_read_b128 v[176:179], v164
	ds_read_b128 v[180:183], v164 offset:1024
	ds_read_b128 v[184:187], v164 offset:2048
	ds_read_b128 v[188:191], v164 offset:3072
	ds_read_b128 v[192:195], v164 offset:4096
	ds_read_b128 v[196:199], v164 offset:5120
	ds_read_b128 v[200:203], v164 offset:6144
	ds_read_b128 v[204:207], v164 offset:7168
	global_load_lds_dwordx4 v128, s[68:69]
	s_add_i32 m0, s38, 0xe000
	s_nop 0
	global_load_lds_dwordx4 v132, s[68:69]
	s_waitcnt vmcnt(8)
	s_waitcnt lgkmcnt(0)
	s_barrier
	s_setprio 1
	s_waitcnt lgkmcnt(0)
	v_mfma_f32_16x16x32_bf16 v[124:127], v[140:143], v[176:179], v[124:127]
	v_mov_b32_e32 v208, v210
	v_mfma_f32_16x16x32_bf16 v[120:123], v[148:151], v[176:179], v[120:123]
	v_mov_b32_e32 v209, v211
	v_mfma_f32_16x16x32_bf16 v[108:111], v[140:143], v[184:187], v[108:111]
	v_mov_b32_e32 v210, v212
	v_mfma_f32_16x16x32_bf16 v[104:107], v[148:151], v[184:187], v[104:107]
	v_mov_b32_e32 v211, v213
	v_mfma_f32_16x16x32_bf16 v[92:95], v[140:143], v[192:195], v[92:95]
	v_mov_b32_e32 v212, v214
	v_mfma_f32_16x16x32_bf16 v[88:91], v[148:151], v[192:195], v[88:91]
	v_mov_b32_e32 v213, v215
	v_mfma_f32_16x16x32_bf16 v[76:79], v[140:143], v[200:203], v[76:79]
	v_mov_b32_e32 v214, v216
	v_mfma_f32_16x16x32_bf16 v[72:75], v[148:151], v[200:203], v[72:75]
	v_mov_b32_e32 v215, v217
	v_mfma_f32_16x16x32_bf16 v[124:127], v[144:147], v[180:183], v[124:127]
	v_mov_b32_e32 v216, v218
	v_mfma_f32_16x16x32_bf16 v[120:123], v[152:155], v[180:183], v[120:123]
	v_mov_b32_e32 v217, v219
	v_mfma_f32_16x16x32_bf16 v[108:111], v[144:147], v[188:191], v[108:111]
	v_mov_b32_e32 v218, v220
	v_mfma_f32_16x16x32_bf16 v[104:107], v[152:155], v[188:191], v[104:107]
	v_mov_b32_e32 v219, v221
	v_mfma_f32_16x16x32_bf16 v[92:95], v[144:147], v[196:199], v[92:95]
	v_mov_b32_e32 v220, v222
	v_mfma_f32_16x16x32_bf16 v[88:91], v[152:155], v[196:199], v[88:91]
	v_mov_b32_e32 v221, v223
	v_mfma_f32_16x16x32_bf16 v[76:79], v[144:147], v[204:207], v[76:79]
	v_mov_b32_e32 v222, v224
	v_mfma_f32_16x16x32_bf16 v[72:75], v[152:155], v[204:207], v[72:75]
	v_mov_b32_e32 v223, v225
	s_setprio 0
	s_setprio 1
	v_mfma_f32_16x16x32_bf16 v[116:119], v[156:159], v[176:179], v[116:119]
	v_mov_b32_e32 v224, v226
	v_mfma_f32_16x16x32_bf16 v[112:115], v[168:171], v[176:179], v[112:115]
	v_mov_b32_e32 v225, v227
	v_mfma_f32_16x16x32_bf16 v[100:103], v[156:159], v[184:187], v[100:103]
	v_mov_b32_e32 v226, v228
	v_mfma_f32_16x16x32_bf16 v[96:99], v[168:171], v[184:187], v[96:99]
	v_mov_b32_e32 v227, v229
	v_mfma_f32_16x16x32_bf16 v[84:87], v[156:159], v[192:195], v[84:87]
	v_mov_b32_e32 v228, v230
	v_mfma_f32_16x16x32_bf16 v[80:83], v[168:171], v[192:195], v[80:83]
	v_mov_b32_e32 v229, v231
	v_mfma_f32_16x16x32_bf16 v[68:71], v[156:159], v[200:203], v[68:71]
	v_mov_b32_e32 v230, v232
	v_mfma_f32_16x16x32_bf16 v[64:67], v[168:171], v[200:203], v[64:67]
	v_mov_b32_e32 v231, v233
	v_mfma_f32_16x16x32_bf16 v[116:119], v[160:163], v[180:183], v[116:119]
	v_mov_b32_e32 v232, v234
	v_mfma_f32_16x16x32_bf16 v[112:115], v[172:175], v[180:183], v[112:115]
	v_mov_b32_e32 v233, v235
	v_mfma_f32_16x16x32_bf16 v[100:103], v[160:163], v[188:191], v[100:103]
	v_mov_b32_e32 v234, v236
	v_mfma_f32_16x16x32_bf16 v[96:99], v[172:175], v[188:191], v[96:99]
	v_mov_b32_e32 v235, v237
	v_mfma_f32_16x16x32_bf16 v[84:87], v[160:163], v[196:199], v[84:87]
	v_mov_b32_e32 v236, v238
	v_mfma_f32_16x16x32_bf16 v[80:83], v[172:175], v[196:199], v[80:83]
	v_mov_b32_e32 v237, v239
	v_mfma_f32_16x16x32_bf16 v[68:71], v[160:163], v[204:207], v[68:71]
	v_mfma_f32_16x16x32_bf16 v[64:67], v[172:175], v[204:207], v[64:67]
	s_setprio 0
	s_barrier
	s_add_i32 s68, s57, s33
	s_mov_b32 m0, s68
	ds_read_b128 v[176:179], v164 offset:16384
	ds_read_b128 v[180:183], v164 offset:17408
	ds_read_b128 v[184:187], v164 offset:18432
	ds_read_b128 v[188:191], v164 offset:19456
	ds_read_b128 v[192:195], v164 offset:20480
	ds_read_b128 v[196:199], v164 offset:21504
	ds_read_b128 v[200:203], v164 offset:22528
	ds_read_b128 v[204:207], v164 offset:23552
	global_load_lds_dwordx4 v166, s[44:45]
	s_add_i32 m0, s68, 0x2000
	s_nop 0
	global_load_lds_dwordx4 v134, s[44:45]
	s_add_i32 s44, s60, s33
	s_mov_b32 m0, s44
	s_nop 0
	global_load_lds_dwordx4 v166, s[46:47]
	s_add_i32 m0, s44, 0x2000
	s_nop 0
	global_load_lds_dwordx4 v134, s[46:47]
	s_mov_b32 m0, s38
	s_nop 0
	global_load_lds_dwordx4 v128, s[42:43]
	s_mov_b32 m0, s39
	s_nop 0
	global_load_lds_dwordx4 v132, s[42:43]
	global_load_dword v238, v250, s[98:99]
	global_load_dword v239, v251, s[98:99]
	s_add_u32 s98, s98, 0x4000
	s_addc_u32 s99, s99, 0
	s_waitcnt vmcnt(10)
	s_waitcnt lgkmcnt(0)
	s_barrier
	s_setprio 1
	s_waitcnt lgkmcnt(0)
	v_mfma_f32_16x16x32_bf16 v[60:63], v[140:143], v[176:179], v[60:63]
	v_mfma_f32_16x16x32_bf16 v[56:59], v[148:151], v[176:179], v[56:59]
	v_mfma_f32_16x16x32_bf16 v[44:47], v[140:143], v[184:187], v[44:47]
	v_mfma_f32_16x16x32_bf16 v[40:43], v[148:151], v[184:187], v[40:43]
	v_mfma_f32_16x16x32_bf16 v[28:31], v[140:143], v[192:195], v[28:31]
	v_mfma_f32_16x16x32_bf16 v[24:27], v[148:151], v[192:195], v[24:27]
	v_mfma_f32_16x16x32_bf16 v[12:15], v[140:143], v[200:203], v[12:15]
	v_mfma_f32_16x16x32_bf16 v[8:11], v[148:151], v[200:203], v[8:11]
	v_mfma_f32_16x16x32_bf16 v[60:63], v[144:147], v[180:183], v[60:63]
	v_mfma_f32_16x16x32_bf16 v[56:59], v[152:155], v[180:183], v[56:59]
	v_mfma_f32_16x16x32_bf16 v[44:47], v[144:147], v[188:191], v[44:47]
	v_mfma_f32_16x16x32_bf16 v[40:43], v[152:155], v[188:191], v[40:43]
	v_mfma_f32_16x16x32_bf16 v[28:31], v[144:147], v[196:199], v[28:31]
	v_mfma_f32_16x16x32_bf16 v[24:27], v[152:155], v[196:199], v[24:27]
	v_mfma_f32_16x16x32_bf16 v[12:15], v[144:147], v[204:207], v[12:15]
	v_mfma_f32_16x16x32_bf16 v[8:11], v[152:155], v[204:207], v[8:11]
	s_setprio 0
	s_setprio 1
	v_mfma_f32_16x16x32_bf16 v[52:55], v[156:159], v[176:179], v[52:55]
	v_mfma_f32_16x16x32_bf16 v[48:51], v[168:171], v[176:179], v[48:51]
	v_mfma_f32_16x16x32_bf16 v[36:39], v[156:159], v[184:187], v[36:39]
	v_mfma_f32_16x16x32_bf16 v[32:35], v[168:171], v[184:187], v[32:35]
	v_mfma_f32_16x16x32_bf16 v[20:23], v[156:159], v[192:195], v[20:23]
	v_mfma_f32_16x16x32_bf16 v[16:19], v[168:171], v[192:195], v[16:19]
	v_mfma_f32_16x16x32_bf16 v[4:7], v[156:159], v[200:203], v[4:7]
	v_mfma_f32_16x16x32_bf16 v[0:3], v[168:171], v[200:203], v[0:3]
	v_mfma_f32_16x16x32_bf16 v[52:55], v[160:163], v[180:183], v[52:55]
	v_mfma_f32_16x16x32_bf16 v[48:51], v[172:175], v[180:183], v[48:51]
	v_mfma_f32_16x16x32_bf16 v[36:39], v[160:163], v[188:191], v[36:39]
	v_mfma_f32_16x16x32_bf16 v[32:35], v[172:175], v[188:191], v[32:35]
	v_mfma_f32_16x16x32_bf16 v[20:23], v[160:163], v[196:199], v[20:23]
	v_mfma_f32_16x16x32_bf16 v[16:19], v[172:175], v[196:199], v[16:19]
	v_mfma_f32_16x16x32_bf16 v[4:7], v[160:163], v[204:207], v[4:7]
	v_mfma_f32_16x16x32_bf16 v[0:3], v[172:175], v[204:207], v[0:3]
	s_setprio 0
	s_barrier
	s_add_i32 s42, 0, 0x18000
	v_add_u32_e32 v130, s42, v129
	s_add_i32 s43, 0, 0x1c000
	ds_read_b128 v[140:143], v130
	ds_read_b128 v[144:147], v130 offset:1024
	ds_read_b128 v[148:151], v130 offset:2048
	ds_read_b128 v[152:155], v130 offset:3072
	v_add_u32_e32 v130, s43, v129
	ds_read_b128 v[156:159], v130
	ds_read_b128 v[160:163], v130 offset:1024
	ds_read_b128 v[168:171], v130 offset:2048
	ds_read_b128 v[172:175], v130 offset:3072
	s_mov_b32 m0, s52
	ds_read_b128 v[176:179], v164 offset:32768
	ds_read_b128 v[180:183], v164 offset:33792
	ds_read_b128 v[184:187], v164 offset:34816
	ds_read_b128 v[188:191], v164 offset:35840
	ds_read_b128 v[192:195], v164 offset:36864
	ds_read_b128 v[196:199], v164 offset:37888
	ds_read_b128 v[200:203], v164 offset:38912
	ds_read_b128 v[204:207], v164 offset:39936
	global_load_lds_dwordx4 v128, s[40:41]
	s_mov_b32 m0, s53
	s_nop 0
	global_load_lds_dwordx4 v132, s[40:41]
	s_waitcnt vmcnt(10)
	s_waitcnt lgkmcnt(0)
	s_barrier
	s_setprio 1
	s_waitcnt lgkmcnt(0)
	v_mfma_f32_16x16x32_bf16 v[124:127], v[140:143], v[176:179], v[124:127]
	v_mfma_f32_16x16x32_bf16 v[120:123], v[148:151], v[176:179], v[120:123]
	v_mfma_f32_16x16x32_bf16 v[108:111], v[140:143], v[184:187], v[108:111]
	v_mfma_f32_16x16x32_bf16 v[104:107], v[148:151], v[184:187], v[104:107]
	v_mfma_f32_16x16x32_bf16 v[92:95], v[140:143], v[192:195], v[92:95]
	v_mfma_f32_16x16x32_bf16 v[88:91], v[148:151], v[192:195], v[88:91]
	v_mfma_f32_16x16x32_bf16 v[76:79], v[140:143], v[200:203], v[76:79]
	v_mfma_f32_16x16x32_bf16 v[72:75], v[148:151], v[200:203], v[72:75]
	v_mfma_f32_16x16x32_bf16 v[124:127], v[144:147], v[180:183], v[124:127]
	v_mfma_f32_16x16x32_bf16 v[120:123], v[152:155], v[180:183], v[120:123]
	v_mfma_f32_16x16x32_bf16 v[108:111], v[144:147], v[188:191], v[108:111]
	v_mfma_f32_16x16x32_bf16 v[104:107], v[152:155], v[188:191], v[104:107]
	v_mfma_f32_16x16x32_bf16 v[92:95], v[144:147], v[196:199], v[92:95]
	v_mfma_f32_16x16x32_bf16 v[88:91], v[152:155], v[196:199], v[88:91]
	v_mfma_f32_16x16x32_bf16 v[76:79], v[144:147], v[204:207], v[76:79]
	v_mfma_f32_16x16x32_bf16 v[72:75], v[152:155], v[204:207], v[72:75]
	s_setprio 0
	s_setprio 1
	v_mfma_f32_16x16x32_bf16 v[116:119], v[156:159], v[176:179], v[116:119]
	v_mfma_f32_16x16x32_bf16 v[112:115], v[168:171], v[176:179], v[112:115]
	v_mfma_f32_16x16x32_bf16 v[100:103], v[156:159], v[184:187], v[100:103]
	v_mfma_f32_16x16x32_bf16 v[96:99], v[168:171], v[184:187], v[96:99]
	v_mfma_f32_16x16x32_bf16 v[84:87], v[156:159], v[192:195], v[84:87]
	v_mfma_f32_16x16x32_bf16 v[80:83], v[168:171], v[192:195], v[80:83]
	v_mfma_f32_16x16x32_bf16 v[68:71], v[156:159], v[200:203], v[68:71]
	v_mfma_f32_16x16x32_bf16 v[64:67], v[168:171], v[200:203], v[64:67]
	v_mfma_f32_16x16x32_bf16 v[116:119], v[160:163], v[180:183], v[116:119]
	v_mfma_f32_16x16x32_bf16 v[112:115], v[172:175], v[180:183], v[112:115]
	v_mfma_f32_16x16x32_bf16 v[100:103], v[160:163], v[188:191], v[100:103]
	v_mfma_f32_16x16x32_bf16 v[96:99], v[172:175], v[188:191], v[96:99]
	v_mfma_f32_16x16x32_bf16 v[84:87], v[160:163], v[196:199], v[84:87]
	v_mfma_f32_16x16x32_bf16 v[80:83], v[172:175], v[196:199], v[80:83]
	v_mfma_f32_16x16x32_bf16 v[68:71], v[160:163], v[204:207], v[68:71]
	v_mfma_f32_16x16x32_bf16 v[64:67], v[172:175], v[204:207], v[64:67]
	s_setprio 0
	s_barrier
; #define PG8_MMA(ai, bj, At, Bt) do { __builtin_amdgcn_s_setprio(1); _Pragma("unroll") for (int m = 0; m < 4; ++m) _Pragma("unroll") for (int n = 0; n < 2; ++n) _Pragma("unroll") for (int k = 0; k < 2; ++k) \
;         acc[ai][bj][m][n] = __builtin_amdgcn_mfma_f32_16x16x32_bf16(Bt[n][k], At[m][k], acc[ai][bj][m][n], 0, 0, 0); __builtin_amdgcn_s_setprio(0); } while (0)
; #define PG8_MMA8(ai, bj, At, Bt) do { __builtin_amdgcn_s_setprio(1); _Pragma("unroll") for (int m = 0; m < 4; ++m) _Pragma("unroll") for (int n = 0; n < 2; ++n) \
;         acc[ai][bj][m][n] = __builtin_amdgcn_mfma_scale_f32_16x16x128_f8f6f4(PG8_CAT(Bt[n][0], Bt[n][1]), PG8_CAT(At[m][0], At[m][1]), acc[ai][bj][m][n], 0, 0, 0, 0, 0, 0); __builtin_amdgcn_s_setprio(0); } while (0)
; #define PG8_BAR __builtin_amdgcn_s_barrier()
;     ...
;         { const int tmid = (TSW > 0 && TSW < nt) ? TSW : nt;
;           _Pragma("unroll 1") for (int t = 0; t < tmid; t += 2) { PG8_BODY(PG8_MMA) }
;           if constexpr (TSW > 0) { _Pragma("unroll 1") for (int t = tmid; t < nt; t += 2) { PG8_BODY(PG8_MMA8) } } }
;     ...
;         if constexpr (ALIGN_EPI) { if (wr == 0) PG8_BAR; }
	s_add_i32 s40, s42, s33
	s_mov_b32 m0, s40
	ds_read_b128 v[176:179], v164 offset:49152
	ds_read_b128 v[180:183], v164 offset:50176
	ds_read_b128 v[184:187], v164 offset:51200
	ds_read_b128 v[188:191], v164 offset:52224
	ds_read_b128 v[192:195], v164 offset:53248
	ds_read_b128 v[196:199], v164 offset:54272
	ds_read_b128 v[200:203], v164 offset:55296
	ds_read_b128 v[204:207], v164 offset:56320
	global_load_lds_dwordx4 v166, s[36:37]
	s_add_i32 m0, s40, 0x2000
	s_nop 0
	global_load_lds_dwordx4 v134, s[36:37]
	s_add_i32 s36, s43, s33
	s_mov_b32 m0, s36
	s_nop 0
	global_load_lds_dwordx4 v166, s[28:29]
	s_add_i32 m0, s36, 0x2000
	s_nop 0
	global_load_lds_dwordx4 v134, s[28:29]
	s_mov_b32 m0, s14
	s_nop 0
	global_load_lds_dwordx4 v128, s[34:35]
	s_mov_b32 m0, s15
	s_nop 0
	global_load_lds_dwordx4 v132, s[34:35]
	s_waitcnt vmcnt(10)
	s_waitcnt lgkmcnt(0)
	s_barrier
	s_setprio 1
	s_waitcnt lgkmcnt(0)
	v_mfma_f32_16x16x32_bf16 v[60:63], v[140:143], v[176:179], v[60:63]
	v_mfma_f32_16x16x32_bf16 v[56:59], v[148:151], v[176:179], v[56:59]
	v_mfma_f32_16x16x32_bf16 v[44:47], v[140:143], v[184:187], v[44:47]
	v_mfma_f32_16x16x32_bf16 v[40:43], v[148:151], v[184:187], v[40:43]
	v_mfma_f32_16x16x32_bf16 v[28:31], v[140:143], v[192:195], v[28:31]
	v_mfma_f32_16x16x32_bf16 v[24:27], v[148:151], v[192:195], v[24:27]
	v_mfma_f32_16x16x32_bf16 v[12:15], v[140:143], v[200:203], v[12:15]
	v_mfma_f32_16x16x32_bf16 v[8:11], v[148:151], v[200:203], v[8:11]
	v_mfma_f32_16x16x32_bf16 v[60:63], v[144:147], v[180:183], v[60:63]
	v_mfma_f32_16x16x32_bf16 v[56:59], v[152:155], v[180:183], v[56:59]
	v_mfma_f32_16x16x32_bf16 v[44:47], v[144:147], v[188:191], v[44:47]
	v_mfma_f32_16x16x32_bf16 v[40:43], v[152:155], v[188:191], v[40:43]
	v_mfma_f32_16x16x32_bf16 v[28:31], v[144:147], v[196:199], v[28:31]
	v_mfma_f32_16x16x32_bf16 v[24:27], v[152:155], v[196:199], v[24:27]
	v_mfma_f32_16x16x32_bf16 v[12:15], v[144:147], v[204:207], v[12:15]
	v_mfma_f32_16x16x32_bf16 v[8:11], v[152:155], v[204:207], v[8:11]
	s_setprio 0
	s_setprio 1
	v_mfma_f32_16x16x32_bf16 v[52:55], v[156:159], v[176:179], v[52:55]
	v_mfma_f32_16x16x32_bf16 v[48:51], v[168:171], v[176:179], v[48:51]
	v_mfma_f32_16x16x32_bf16 v[36:39], v[156:159], v[184:187], v[36:39]
	v_mfma_f32_16x16x32_bf16 v[32:35], v[168:171], v[184:187], v[32:35]
	v_mfma_f32_16x16x32_bf16 v[20:23], v[156:159], v[192:195], v[20:23]
	v_mfma_f32_16x16x32_bf16 v[16:19], v[168:171], v[192:195], v[16:19]
	v_mfma_f32_16x16x32_bf16 v[4:7], v[156:159], v[200:203], v[4:7]
	v_mfma_f32_16x16x32_bf16 v[0:3], v[168:171], v[200:203], v[0:3]
	v_mfma_f32_16x16x32_bf16 v[52:55], v[160:163], v[180:183], v[52:55]
	v_mfma_f32_16x16x32_bf16 v[48:51], v[172:175], v[180:183], v[48:51]
	v_mfma_f32_16x16x32_bf16 v[36:39], v[160:163], v[188:191], v[36:39]
	v_mfma_f32_16x16x32_bf16 v[32:35], v[172:175], v[188:191], v[32:35]
	v_mfma_f32_16x16x32_bf16 v[20:23], v[160:163], v[196:199], v[20:23]
	v_mfma_f32_16x16x32_bf16 v[16:19], v[172:175], v[196:199], v[16:19]
	v_mfma_f32_16x16x32_bf16 v[4:7], v[160:163], v[204:207], v[4:7]
	v_mfma_f32_16x16x32_bf16 v[0:3], v[172:175], v[204:207], v[0:3]
	s_setprio 0
	s_barrier
	s_add_i32 s67, s67, 2
	s_add_u32 s61, s61, 0x100
	s_addc_u32 s66, s66, 0
	s_cmp_gt_u32 s67, 29
	s_mov_b64 s[28:29], s[30:31]
	s_cbranch_scc0 .LBB0_182
	s_and_b64 vcc, exec, s[16:17]
	s_cbranch_vccz .LBB0_185
	s_barrier
;     __device__ __forceinline__ void operator()(const f32x4 (&acc)[2][2][4][2], const Unit& u, int wr, int wc, int fr, int fq) const {
;         { int l_ = (int)lane_id_fresh(); asm volatile("" : "+v"(l_)); fr = l_ & 15; fq = l_ >> 4; }
;         const int row0 = u.pm * BM + wr * 64 + fr; int colt = u.pn * BM; bf16_t* base = O;
;         float sc = 1.f; bool hm = false, k8 = false; if (split_cols) { const int t = colt / split_cols; base += (size_t)t * split_stride; colt -= t * split_cols; if (t == 0) sc = scale0; hm = HM && t < 3; k8 = HM && (t == 1 || t == 2); }
;         const int col0 = colt + wc * 32 + 8 * fq, gcol0 = u.pn * BM + wc * 32 + 8 * fq;
;         const size_t bstep = hm ? (size_t)4096 * 128 : (size_t)HALF;
;         f32x4 cv[2][2];
; #pragma unroll
;         for (int bj = 0; bj < 2; ++bj)
; #pragma unroll
;             for (int n = 0; n < 2; ++n) cv[bj][n] = CS ? *(const f32x4*)(cs + gcol0 + bj * HALF + 4 * n) : (f32x4){1.f, 1.f, 1.f, 1.f};
;         float rsv[2][4];
; #pragma unroll
;         for (int ai = 0; ai < 2; ++ai)
; #pragma unroll
;             for (int m = 0; m < 4; ++m) rsv[ai][m] = RS ? rs[row0 + ai * HALF + m * 16] : 1.0f;
; __device__ __forceinline__ void p0_transpose_item(const float* W, int ldw, int col_off, int K, int N, const float* rs, bf16_t* WT, LAS float* scr, int item, int lane) {
;     const int nblk = N / 32, kb = item / nblk, nb = item % nblk, k0 = 64 * kb, n0 = 32 * nb;
;     const int r8 = lane >> 3, c4 = (lane & 7) * 4;
;     f32x4 v[8]; float sc[8];
; #pragma unroll
;     for (int i = 0; i < 8; ++i) { const int kk = 8 * i + r8; v[i] = __builtin_nontemporal_load((const GAS f32x4*)(W + (size_t)(k0 + kk) * ldw + col_off + n0 + c4)); sc[i] = rs ? rs[k0 + kk] : 1.0f; }
; #pragma unroll
;     for (int i = 0; i < 8; ++i) { LAS float* d = scr + (8 * i + r8) * 33 + c4; d[0] = v[i].x * sc[i]; d[1] = v[i].y * sc[i]; d[2] = v[i].z * sc[i]; d[3] = v[i].w * sc[i]; }
;     LDS_WAIT();
;     const int c = lane & 7;
; #pragma unroll
;     for (int j = 0; j < 4; ++j) { const int n = (lane >> 3) + 8 * j; const LAS float* s = scr + (8 * c) * 33 + n;
;         v4u o; o.x = pk2(s[0 * 33], s[1 * 33]); o.y = pk2(s[2 * 33], s[3 * 33]); o.z = pk2(s[4 * 33], s[5 * 33]); o.w = pk2(s[6 * 33], s[7 * 33]);
;         *(GAS v4u*)(WT + (size_t)(n0 + n) * K + k0 + 8 * c) = o; }
;     LDS_WAIT();
; }
.LBB0_185:
	s_waitcnt vmcnt(8)
	v_readlane_b32 s98, v252, 5
	s_sub_i32 s99, s54, 1
	s_lshl_b32 s99, s99, 11
	s_add_i32 s98, s98, s99
	s_and_b32 s98, s98, 0x1fff
	s_lshr_b32 s99, s98, 6
	s_and_b32 s98, s98, 63
	s_lshl_b32 s98, s98, 19
	s_lshl_b32 s99, s99, 7
	s_add_u32 s98, s98, s99
	v_readlane_b32 s100, v252, 2
	v_readlane_b32 s101, v252, 3
	s_add_u32 s100, s100, s98
	s_addc_u32 s101, s101, 0
	v_mbcnt_lo_u32_b32 v249, -1, 0
	v_mbcnt_hi_u32_b32 v249, -1, v249
	v_lshrrev_b32_e32 v248, 5, v249
	v_and_b32_e32 v249, 31, v249
	v_lshlrev_b32_e32 v248, 6, v248
	v_lshl_or_b32 v248, v249, 14, v248
	v_cvt_pk_bf16_f32 v208, v208, v209
	v_cvt_pk_bf16_f32 v209, v210, v211
	v_cvt_pk_bf16_f32 v210, v212, v213
	v_cvt_pk_bf16_f32 v211, v214, v215
	v_cvt_pk_bf16_f32 v212, v216, v217
	v_cvt_pk_bf16_f32 v213, v218, v219
	v_cvt_pk_bf16_f32 v214, v220, v221
	v_cvt_pk_bf16_f32 v215, v222, v223
	v_cvt_pk_bf16_f32 v216, v224, v225
	v_cvt_pk_bf16_f32 v217, v226, v227
	v_cvt_pk_bf16_f32 v218, v228, v229
	v_cvt_pk_bf16_f32 v219, v230, v231
	v_cvt_pk_bf16_f32 v220, v232, v233
	v_cvt_pk_bf16_f32 v221, v234, v235
	v_cvt_pk_bf16_f32 v222, v236, v237
	v_cvt_pk_bf16_f32 v223, v238, v239
	global_store_dwordx4 v248, v[208:211], s[100:101]
	global_store_dwordx4 v248, v[212:215], s[100:101] offset:16
	global_store_dwordx4 v248, v[216:219], s[100:101] offset:32
	global_store_dwordx4 v248, v[220:223], s[100:101] offset:48
	s_mov_b32 s5, -1
	s_lshl_b32 s19, s4, 8
	v_mbcnt_lo_u32_b32 v130, s5, 0
	v_mbcnt_hi_u32_b32 v130, s5, v130
	s_lshl_b32 s5, s6, 8
	s_add_i32 s5, s5, s48
	s_ashr_i32 s6, s4, 31
	v_and_or_b32 v140, v130, 15, s5
	v_ashrrev_i32_e32 v141, 31, v140
	v_or_b32_e32 v152, 16, v140
	v_or_b32_e32 v150, 32, v140
	v_or_b32_e32 v146, 48, v140
	v_lshl_add_u64 v[142:143], v[140:141], 2, s[12:13]
	v_ashrrev_i32_e32 v153, 31, v152
	v_ashrrev_i32_e32 v151, 31, v150
	v_ashrrev_i32_e32 v147, 31, v146
	v_lshl_add_u64 v[144:145], v[152:153], 2, s[12:13]
	v_lshl_add_u64 v[148:149], v[150:151], 2, s[12:13]
	v_lshl_add_u64 v[154:155], v[146:147], 2, s[12:13]
	v_mov_b32_e32 v158, v240
	v_mov_b32_e32 v173, v241
	v_mov_b32_e32 v172, v242
	v_mov_b32_e32 v171, v243
	v_mov_b32_e32 v170, v244
	v_mov_b32_e32 v169, v245
	v_mov_b32_e32 v168, v246
	v_mov_b32_e32 v167, v247
	s_lshl_b32 vcc_lo, s20, 8
	s_add_i32 vcc_lo, vcc_lo, s48
	s_cmp_lg_u64 s[8:9], 0
	s_cselect_b32 vcc_lo, vcc_lo, s5
	v_and_or_b32 v248, v140, 15, vcc_lo
	v_mov_b32_e32 v249, 0
	v_lshl_add_u64 v[248:249], v[248:249], 2, s[12:13]
	global_load_dword v240, v[248:249], off
	global_load_dword v241, v[248:249], off offset:64
	global_load_dword v242, v[248:249], off offset:128
	global_load_dword v243, v[248:249], off offset:192
	global_load_dword v244, v[248:249], off offset:512
	global_load_dword v245, v[248:249], off offset:576
	global_load_dword v246, v[248:249], off offset:640
	global_load_dword v247, v[248:249], off offset:704
	s_lshr_b32 s6, s6, 30
	s_add_i32 s6, s4, s6
	s_ashr_i32 s36, s6, 2
	s_ashr_i32 s37, s36, 31
	s_lshl_b64 s[6:7], s[36:37], 25
	s_add_u32 s28, s84, s6
	s_addc_u32 s29, s85, s7
	s_lshl_b32 s6, s36, 10
	s_sub_i32 s19, s19, s6
	s_cmp_lt_i32 s4, 12
	s_cselect_b64 s[6:7], -1, 0
	s_cmp_gt_i32 s4, 11
	v_ashrrev_i32_e32 v130, 1, v130
	s_cselect_b64 s[30:31], -1, 0
	v_and_b32_e32 v156, -8, v130
	s_or_b32 s21, s19, s50
	v_add_u32_e32 v142, s21, v156
	s_add_u32 s34, s28, s50
	s_addc_u32 s35, s29, 0
	v_ashrrev_i32_e32 v143, 31, v142
	v_lshl_add_u64 v[142:143], v[142:143], 1, s[28:29]
	s_add_u32 s28, s34, s50
	s_addc_u32 s29, s35, 0
	s_mov_b64 s[40:41], -1
	s_and_b64 vcc, exec, s[30:31]
	v_lshlrev_b32_e32 v159, 7, v140
	s_cbranch_vccz .LBB0_187
	v_lshlrev_b64 v[144:145], 11, v[140:141]
	v_lshl_add_u64 v[154:155], v[142:143], 0, v[144:145]
	v_and_b32_e32 v130, 0x7e780, v159
	s_mov_b64 s[40:41], 0
